# speedup vs baseline: 1.0310x; 1.0146x over previous
; #define LAS __attribute__((address_space(3)))
; __device__ __forceinline__ unsigned cvt_pk_bf16(float lo, float hi) { const f32x2 v = {lo, hi}; const bf16x2_t b = __builtin_convertvector(v, bf16x2_t); return __builtin_bit_cast(unsigned, b); }
; __device__ __forceinline__ void softmax_pv(f32x16& s0, f32x16& s1, float& mref, f32x16& negm, float& lsum, f32x16 (&o)[2], LAS float* fac, const bf16x8 (&vf)[2][4], bool first, int r32, int hi) {
;     ...
;     float ps0 = 0.f, ps1 = 0.f;
; #pragma unroll
;     for (int r = 0; r < 16; ++r) { s0[r] = __builtin_amdgcn_exp2f(s0[r]); s1[r] = __builtin_amdgcn_exp2f(s1[r]); ps0 += s0[r]; ps1 += s1[r]; }
;     lsum += ps0 + ps1;
;     bf16x8 pa[4];
; #pragma unroll
;     for (int k = 0; k < 4; ++k) {
;         const f32x16& s = (k < 2) ? s0 : s1; const int rb = 8 * (k & 1);
;         u32x4 w; w.x = cvt_pk_bf16(s[rb + 0], s[rb + 1]); w.y = cvt_pk_bf16(s[rb + 2], s[rb + 3]); w.z = cvt_pk_bf16(s[rb + 4], s[rb + 5]); w.w = cvt_pk_bf16(s[rb + 6], s[rb + 7]);
;         pa[k] = __builtin_bit_cast(bf16x8, w);
;     }
; #pragma unroll
;     for (int k = 0; k < 4; ++k) {
;         o[0] = __builtin_amdgcn_mfma_f32_32x32x16_bf16(pa[k], vf[0][k], o[0], 0, 0, 0);
;         o[1] = __builtin_amdgcn_mfma_f32_32x32x16_bf16(pa[k], vf[1][k], o[1], 0, 0, 0);
;     }
; template <bool DIFF>
; __device__ __forceinline__ void attn_item(const Params& p, int l, int I, LAS unsigned char* lds, const int tid) {
;     ...
;             bf16x8 kg[2][2];
; #pragma unroll
;             for (int d0 = 0; d0 < 2; ++d0) { kg[d0][0] = *(const LAS bf16x8*)(kb + 4096 + d0 * 2048); kg[d0][1] = *(const LAS bf16x8*)(kb + 4096 + d0 * 2048 + 512); }
; #pragma unroll
;             for (int d0 = 0; d0 < 2; ++d0) {
;                 s0 = __builtin_amdgcn_mfma_f32_32x32x16_bf16(kg[d0][0], qf[2 + d0], s0, 0, 0, 0);
;                 s1 = __builtin_amdgcn_mfma_f32_32x32x16_bf16(kg[d0][1], qf[2 + d0], s1, 0, 0, 0);
.Ldr_cont_00:
	v_exp_f32_e32 v80, v80
	v_exp_f32_e32 v81, v81
	v_exp_f32_e32 v82, v82
	v_exp_f32_e32 v83, v83
	v_exp_f32_e32 v84, v84
	v_exp_f32_e32 v85, v85
	v_exp_f32_e32 v86, v86
	v_exp_f32_e32 v87, v87
	v_cvt_pk_bf16_f32 v210, v80, v81
	v_cvt_pk_bf16_f32 v211, v82, v83
	v_cvt_pk_bf16_f32 v212, v84, v85
	v_cvt_pk_bf16_f32 v213, v86, v87
	v_mfma_f32_4x4x4_16b_bf16 v[164:167], v[210:211], v[214:215], v[164:167]
	v_exp_f32_e32 v88, v88
	v_exp_f32_e32 v89, v89
	v_mfma_f32_4x4x4_16b_bf16 v[164:167], v[212:213], v[214:215], v[164:167]
	v_exp_f32_e32 v90, v90
	v_exp_f32_e32 v91, v91
	v_mfma_f32_32x32x16_bf16 v[32:47], v[210:213], v[128:131], v[32:47]
	v_exp_f32_e32 v92, v92
	v_exp_f32_e32 v93, v93
	v_exp_f32_e32 v94, v94
	v_exp_f32_e32 v95, v95
	v_mfma_f32_32x32x16_bf16 v[48:63], v[210:213], v[144:147], v[48:63]
	v_cvt_pk_bf16_f32 v248, v88, v89
	v_cvt_pk_bf16_f32 v249, v90, v91
	v_cvt_pk_bf16_f32 v250, v92, v93
	v_cvt_pk_bf16_f32 v251, v94, v95
	v_mfma_f32_4x4x4_16b_bf16 v[164:167], v[248:249], v[214:215], v[164:167]
	v_exp_f32_e32 v64, v64
	v_exp_f32_e32 v65, v65
	v_mfma_f32_4x4x4_16b_bf16 v[164:167], v[250:251], v[214:215], v[164:167]
	v_exp_f32_e32 v66, v66
	v_exp_f32_e32 v67, v67
	s_waitcnt lgkmcnt(12)
	v_mfma_f32_32x32x16_bf16 v[32:47], v[248:251], v[132:135], v[32:47]
	v_exp_f32_e32 v68, v68
	v_exp_f32_e32 v69, v69
	v_mfma_f32_32x32x16_bf16 v[48:63], v[248:251], v[148:151], v[48:63]
	s_waitcnt lgkmcnt(8)
	v_mfma_f32_32x32x16_bf16 v[80:95], v[234:237], v[120:123], v[218:233]
	v_exp_f32_e32 v70, v70
	v_exp_f32_e32 v71, v71
	v_mfma_f32_32x32x16_bf16 v[80:95], v[242:245], v[124:127], v[80:95]
	v_cvt_pk_bf16_f32 v210, v64, v65
	v_cvt_pk_bf16_f32 v211, v66, v67
	v_cvt_pk_bf16_f32 v212, v68, v69
	v_cvt_pk_bf16_f32 v213, v70, v71
	v_mfma_f32_4x4x4_16b_bf16 v[164:167], v[210:211], v[214:215], v[164:167]
	v_exp_f32_e32 v72, v72
	v_exp_f32_e32 v73, v73
	v_mfma_f32_4x4x4_16b_bf16 v[164:167], v[212:213], v[214:215], v[164:167]
	v_exp_f32_e32 v74, v74
	v_exp_f32_e32 v75, v75
	s_waitcnt lgkmcnt(4)
	v_mfma_f32_32x32x16_bf16 v[32:47], v[210:213], v[136:139], v[32:47]
	v_exp_f32_e32 v76, v76
	v_exp_f32_e32 v77, v77
	v_exp_f32_e32 v78, v78
	v_exp_f32_e32 v79, v79
	v_mfma_f32_32x32x16_bf16 v[48:63], v[210:213], v[152:155], v[48:63]
	v_cvt_pk_bf16_f32 v248, v72, v73
	v_cvt_pk_bf16_f32 v249, v74, v75
	v_cvt_pk_bf16_f32 v250, v76, v77
	v_cvt_pk_bf16_f32 v251, v78, v79
	v_mfma_f32_4x4x4_16b_bf16 v[164:167], v[248:249], v[214:215], v[164:167]
	s_nop 1
	v_mfma_f32_4x4x4_16b_bf16 v[164:167], v[250:251], v[214:215], v[164:167]
	s_cmp_eq_u32 s34, 0
	s_cbranch_scc1 .Ldr_first_01
.Ldr_cont_01:
	v_exp_f32_e32 v80, v80
	v_exp_f32_e32 v81, v81
	v_mfma_f32_32x32x16_bf16 v[64:79], v[238:241], v[120:123], v[218:233]
	v_exp_f32_e32 v82, v82
	v_exp_f32_e32 v83, v83
	v_mfma_f32_32x32x16_bf16 v[64:79], v[188:191], v[124:127], v[64:79]
	v_exp_f32_e32 v84, v84
	v_exp_f32_e32 v85, v85
	s_waitcnt lgkmcnt(0)
	v_mfma_f32_32x32x16_bf16 v[32:47], v[248:251], v[140:143], v[32:47]
	v_exp_f32_e32 v86, v86
	v_exp_f32_e32 v87, v87
	v_mfma_f32_32x32x16_bf16 v[48:63], v[248:251], v[156:159], v[48:63]
	v_cvt_pk_bf16_f32 v210, v80, v81
	v_cvt_pk_bf16_f32 v211, v82, v83
	v_cvt_pk_bf16_f32 v212, v84, v85
	v_cvt_pk_bf16_f32 v213, v86, v87
	v_mfma_f32_4x4x4_16b_bf16 v[172:175], v[210:211], v[214:215], v[172:175]
.Ldr_join_01:
	ds_read_b128 v[234:237], v187 offset:20480
	ds_read_b128 v[238:241], v187 offset:20992
	ds_read_b128 v[242:245], v187 offset:22528
	ds_read_b128 v[188:191], v187 offset:23040
	v_exp_f32_e32 v88, v88
	v_exp_f32_e32 v89, v89
	v_mfma_f32_4x4x4_16b_bf16 v[172:175], v[212:213], v[214:215], v[172:175]
	v_exp_f32_e32 v90, v90
	v_exp_f32_e32 v91, v91
	v_mfma_f32_32x32x16_bf16 v[0:15], v[210:213], v[128:131], v[0:15]
	v_exp_f32_e32 v92, v92
	v_exp_f32_e32 v93, v93
	v_exp_f32_e32 v94, v94
	v_exp_f32_e32 v95, v95
	v_mfma_f32_32x32x16_bf16 v[16:31], v[210:213], v[144:147], v[16:31]
	v_cvt_pk_bf16_f32 v248, v88, v89
	v_cvt_pk_bf16_f32 v249, v90, v91
	v_cvt_pk_bf16_f32 v250, v92, v93
	v_cvt_pk_bf16_f32 v251, v94, v95
	v_mfma_f32_4x4x4_16b_bf16 v[172:175], v[248:249], v[214:215], v[172:175]
	v_exp_f32_e32 v64, v64
	v_exp_f32_e32 v65, v65
	v_mfma_f32_4x4x4_16b_bf16 v[172:175], v[250:251], v[214:215], v[172:175]
	v_exp_f32_e32 v66, v66
	v_exp_f32_e32 v67, v67
	v_mfma_f32_32x32x16_bf16 v[0:15], v[248:251], v[132:135], v[0:15]
	v_exp_f32_e32 v68, v68
	v_exp_f32_e32 v69, v69
	v_mfma_f32_32x32x16_bf16 v[16:31], v[248:251], v[148:151], v[16:31]
	s_waitcnt lgkmcnt(0)
; #define LAS __attribute__((address_space(3)))
; __device__ __forceinline__ unsigned cvt_pk_bf16(float lo, float hi) { const f32x2 v = {lo, hi}; const bf16x2_t b = __builtin_convertvector(v, bf16x2_t); return __builtin_bit_cast(unsigned, b); }
; __device__ __forceinline__ void softmax_pv(f32x16& s0, f32x16& s1, float& mref, f32x16& negm, float& lsum, f32x16 (&o)[2], LAS float* fac, const bf16x8 (&vf)[2][4], bool first, int r32, int hi) {
;     ...
;     float ps0 = 0.f, ps1 = 0.f;
; #pragma unroll
;     for (int r = 0; r < 16; ++r) { s0[r] = __builtin_amdgcn_exp2f(s0[r]); s1[r] = __builtin_amdgcn_exp2f(s1[r]); ps0 += s0[r]; ps1 += s1[r]; }
;     lsum += ps0 + ps1;
;     bf16x8 pa[4];
; #pragma unroll
;     for (int k = 0; k < 4; ++k) {
;         const f32x16& s = (k < 2) ? s0 : s1; const int rb = 8 * (k & 1);
;         u32x4 w; w.x = cvt_pk_bf16(s[rb + 0], s[rb + 1]); w.y = cvt_pk_bf16(s[rb + 2], s[rb + 3]); w.z = cvt_pk_bf16(s[rb + 4], s[rb + 5]); w.w = cvt_pk_bf16(s[rb + 6], s[rb + 7]);
;         pa[k] = __builtin_bit_cast(bf16x8, w);
;     }
; #pragma unroll
;     for (int k = 0; k < 4; ++k) {
;         o[0] = __builtin_amdgcn_mfma_f32_32x32x16_bf16(pa[k], vf[0][k], o[0], 0, 0, 0);
;         o[1] = __builtin_amdgcn_mfma_f32_32x32x16_bf16(pa[k], vf[1][k], o[1], 0, 0, 0);
;     }
; template <bool DIFF>
; __device__ __forceinline__ void attn_item(const Params& p, int l, int I, LAS unsigned char* lds, const int tid) {
;     ...
;             bf16x8 kg[2][2];
; #pragma unroll
;             for (int d0 = 0; d0 < 2; ++d0) { kg[d0][0] = *(const LAS bf16x8*)(kb + 4096 + d0 * 2048); kg[d0][1] = *(const LAS bf16x8*)(kb + 4096 + d0 * 2048 + 512); }
; #pragma unroll
;             for (int d0 = 0; d0 < 2; ++d0) {
;                 s0 = __builtin_amdgcn_mfma_f32_32x32x16_bf16(kg[d0][0], qf[2 + d0], s0, 0, 0, 0);
;                 s1 = __builtin_amdgcn_mfma_f32_32x32x16_bf16(kg[d0][1], qf[2 + d0], s1, 0, 0, 0);
;             }
;             softmax_pv(s0, s1, mref2, negm2, l2, o2, scr + 32, vf, t == 0, r32, hi);
	v_mfma_f32_32x32x16_bf16 v[80:95], v[234:237], v[104:107], v[194:209]
	v_exp_f32_e32 v70, v70
	v_exp_f32_e32 v71, v71
	v_mfma_f32_32x32x16_bf16 v[80:95], v[242:245], v[112:115], v[80:95]
	v_cvt_pk_bf16_f32 v210, v64, v65
	v_cvt_pk_bf16_f32 v211, v66, v67
	v_cvt_pk_bf16_f32 v212, v68, v69
	v_cvt_pk_bf16_f32 v213, v70, v71
	v_mfma_f32_4x4x4_16b_bf16 v[172:175], v[210:211], v[214:215], v[172:175]
	v_exp_f32_e32 v72, v72
	v_exp_f32_e32 v73, v73
	v_mfma_f32_4x4x4_16b_bf16 v[172:175], v[212:213], v[214:215], v[172:175]
	v_exp_f32_e32 v74, v74
	v_exp_f32_e32 v75, v75
	v_mfma_f32_32x32x16_bf16 v[0:15], v[210:213], v[136:139], v[0:15]
	v_exp_f32_e32 v76, v76
	v_exp_f32_e32 v77, v77
	v_exp_f32_e32 v78, v78
	v_exp_f32_e32 v79, v79
	v_mfma_f32_32x32x16_bf16 v[16:31], v[210:213], v[152:155], v[16:31]
	v_cvt_pk_bf16_f32 v248, v72, v73
	v_cvt_pk_bf16_f32 v249, v74, v75
	v_cvt_pk_bf16_f32 v250, v76, v77
	v_cvt_pk_bf16_f32 v251, v78, v79
	v_mfma_f32_4x4x4_16b_bf16 v[172:175], v[248:249], v[214:215], v[172:175]
	s_nop 1
	v_mfma_f32_4x4x4_16b_bf16 v[172:175], v[250:251], v[214:215], v[172:175]
	ds_read_b64_tr_b16 v[128:129], v163 offset:32768
	ds_read_b64_tr_b16 v[130:131], v163 offset:33280
	ds_read_b64_tr_b16 v[144:145], v163 offset:36864
	ds_read_b64_tr_b16 v[146:147], v163 offset:37376
	ds_read_b64_tr_b16 v[132:133], v163 offset:33792
	ds_read_b64_tr_b16 v[134:135], v163 offset:34304
	ds_read_b64_tr_b16 v[148:149], v163 offset:37888
	ds_read_b64_tr_b16 v[150:151], v163 offset:38400
	v_exp_f32_e32 v80, v80
	v_exp_f32_e32 v81, v81
	v_mfma_f32_32x32x16_bf16 v[64:79], v[238:241], v[104:107], v[194:209]
	v_exp_f32_e32 v82, v82
	v_exp_f32_e32 v83, v83
	v_mfma_f32_32x32x16_bf16 v[64:79], v[188:191], v[112:115], v[64:79]
	v_exp_f32_e32 v84, v84
	v_exp_f32_e32 v85, v85
	v_mfma_f32_32x32x16_bf16 v[0:15], v[248:251], v[140:143], v[0:15]
	v_exp_f32_e32 v86, v86
	v_exp_f32_e32 v87, v87
	v_mfma_f32_32x32x16_bf16 v[16:31], v[248:251], v[156:159], v[16:31]
	v_cvt_pk_bf16_f32 v210, v80, v81
	v_cvt_pk_bf16_f32 v211, v82, v83
	v_cvt_pk_bf16_f32 v212, v84, v85
	v_cvt_pk_bf16_f32 v213, v86, v87
	v_mfma_f32_4x4x4_16b_bf16 v[164:167], v[210:211], v[214:215], v[164:167]
	ds_read_b128 v[234:237], v187 offset:24576
	ds_read_b128 v[238:241], v187 offset:25088
	ds_read_b128 v[242:245], v187 offset:26624
	ds_read_b128 v[188:191], v187 offset:27136
	s_waitcnt lgkmcnt(7)
	ds_read_b64_tr_b16 v[136:137], v163 offset:34816
	ds_read_b64_tr_b16 v[138:139], v163 offset:35328
	ds_read_b64_tr_b16 v[152:153], v163 offset:38912
	ds_read_b64_tr_b16 v[154:155], v163 offset:39424
	ds_read_b64_tr_b16 v[140:141], v163 offset:35840
	ds_read_b64_tr_b16 v[142:143], v163 offset:36352
	ds_read_b64_tr_b16 v[156:157], v163 offset:39936
	ds_read_b64_tr_b16 v[158:159], v163 offset:40448
	v_exp_f32_e32 v88, v88
	v_exp_f32_e32 v89, v89
	v_mfma_f32_4x4x4_16b_bf16 v[164:167], v[212:213], v[214:215], v[164:167]
	v_exp_f32_e32 v90, v90
	v_exp_f32_e32 v91, v91
	v_mfma_f32_32x32x16_bf16 v[32:47], v[210:213], v[128:131], v[32:47]
	v_exp_f32_e32 v92, v92
	v_exp_f32_e32 v93, v93
	v_exp_f32_e32 v94, v94
	v_exp_f32_e32 v95, v95
	v_mfma_f32_32x32x16_bf16 v[48:63], v[210:213], v[144:147], v[48:63]
	v_cvt_pk_bf16_f32 v248, v88, v89
	v_cvt_pk_bf16_f32 v249, v90, v91
	v_cvt_pk_bf16_f32 v250, v92, v93
	v_cvt_pk_bf16_f32 v251, v94, v95
	v_mfma_f32_4x4x4_16b_bf16 v[164:167], v[248:249], v[214:215], v[164:167]
	v_exp_f32_e32 v64, v64
	v_exp_f32_e32 v65, v65
	v_mfma_f32_4x4x4_16b_bf16 v[164:167], v[250:251], v[214:215], v[164:167]
	v_exp_f32_e32 v66, v66
	v_exp_f32_e32 v67, v67
	s_waitcnt lgkmcnt(12)
	v_mfma_f32_32x32x16_bf16 v[32:47], v[248:251], v[132:135], v[32:47]
	v_exp_f32_e32 v68, v68
	v_exp_f32_e32 v69, v69
	v_mfma_f32_32x32x16_bf16 v[48:63], v[248:251], v[148:151], v[48:63]
	s_waitcnt lgkmcnt(8)
; __device__ __forceinline__ unsigned cvt_pk_bf16(float lo, float hi) { const f32x2 v = {lo, hi}; const bf16x2_t b = __builtin_convertvector(v, bf16x2_t); return __builtin_bit_cast(unsigned, b); }
; __device__ __forceinline__ int crow(int r, int hi) { return (r & 3) + 8 * (r >> 2) + 4 * hi; }
; __device__ __forceinline__ void softmax_pv(f32x16& s0, f32x16& s1, float& mref, f32x16& negm, float& lsum, f32x16 (&o)[2], LAS float* fac, const bf16x8 (&vf)[2][4], bool first, int r32, int hi) {
;     ...
;     if (__builtin_expect(first || __any(mx > 16.0f), 0)) {
;         const float d = first ? mx : fmaxf(mx, 0.f);
;         const float f = __builtin_amdgcn_exp2f(-d);
;         lsum *= f; mref += d;
; #pragma unroll
;         for (int r = 0; r < 16; ++r) { s0[r] -= d; s1[r] -= d; negm[r] = -mref; }
;         if (hi == 0) fac[r32] = f;
;         asm volatile("s_waitcnt lgkmcnt(0)" ::: "memory");
; #pragma unroll
;         for (int r = 0; r < 16; ++r) { const float ff = fac[crow(r, hi)]; o[0][r] *= ff; o[1][r] *= ff; }
;     }
;     float ps0 = 0.f, ps1 = 0.f;
; #pragma unroll
;     for (int r = 0; r < 16; ++r) { s0[r] = __builtin_amdgcn_exp2f(s0[r]); s1[r] = __builtin_amdgcn_exp2f(s1[r]); ps0 += s0[r]; ps1 += s1[r]; }
;     lsum += ps0 + ps1;
;     bf16x8 pa[4];
; #pragma unroll
;     for (int k = 0; k < 4; ++k) {
;         const f32x16& s = (k < 2) ? s0 : s1; const int rb = 8 * (k & 1);
;         u32x4 w; w.x = cvt_pk_bf16(s[rb + 0], s[rb + 1]); w.y = cvt_pk_bf16(s[rb + 2], s[rb + 3]); w.z = cvt_pk_bf16(s[rb + 4], s[rb + 5]); w.w = cvt_pk_bf16(s[rb + 6], s[rb + 7]);
;         pa[k] = __builtin_bit_cast(bf16x8, w);
;     }
; #pragma unroll
;     for (int k = 0; k < 4; ++k) {
;         o[0] = __builtin_amdgcn_mfma_f32_32x32x16_bf16(pa[k], vf[0][k], o[0], 0, 0, 0);
;         o[1] = __builtin_amdgcn_mfma_f32_32x32x16_bf16(pa[k], vf[1][k], o[1], 0, 0, 0);
;     }
	v_mfma_f32_32x32x16_bf16 v[80:95], v[234:237], v[120:123], v[218:233]
	v_exp_f32_e32 v70, v70
	v_exp_f32_e32 v71, v71
	v_mfma_f32_32x32x16_bf16 v[80:95], v[242:245], v[124:127], v[80:95]
	v_cvt_pk_bf16_f32 v210, v64, v65
	v_cvt_pk_bf16_f32 v211, v66, v67
	v_cvt_pk_bf16_f32 v212, v68, v69
	v_cvt_pk_bf16_f32 v213, v70, v71
	v_mfma_f32_4x4x4_16b_bf16 v[164:167], v[210:211], v[214:215], v[164:167]
	v_exp_f32_e32 v72, v72
	v_exp_f32_e32 v73, v73
	v_mfma_f32_4x4x4_16b_bf16 v[164:167], v[212:213], v[214:215], v[164:167]
	v_exp_f32_e32 v74, v74
	v_exp_f32_e32 v75, v75
	s_waitcnt lgkmcnt(4)
	v_mfma_f32_32x32x16_bf16 v[32:47], v[210:213], v[136:139], v[32:47]
	v_exp_f32_e32 v76, v76
	v_exp_f32_e32 v77, v77
	v_exp_f32_e32 v78, v78
	v_exp_f32_e32 v79, v79
	v_mfma_f32_32x32x16_bf16 v[48:63], v[210:213], v[152:155], v[48:63]
	v_cvt_pk_bf16_f32 v248, v72, v73
	v_cvt_pk_bf16_f32 v249, v74, v75
	v_cvt_pk_bf16_f32 v250, v76, v77
	v_cvt_pk_bf16_f32 v251, v78, v79
	v_mfma_f32_4x4x4_16b_bf16 v[164:167], v[248:249], v[214:215], v[164:167]
	s_nop 1
	v_mfma_f32_4x4x4_16b_bf16 v[164:167], v[250:251], v[214:215], v[164:167]
	v_exp_f32_e32 v80, v80
	v_exp_f32_e32 v81, v81
	v_mfma_f32_32x32x16_bf16 v[64:79], v[238:241], v[120:123], v[218:233]
	v_exp_f32_e32 v82, v82
	v_exp_f32_e32 v83, v83
	v_mfma_f32_32x32x16_bf16 v[64:79], v[188:191], v[124:127], v[64:79]
	v_exp_f32_e32 v84, v84
	v_exp_f32_e32 v85, v85
	s_waitcnt lgkmcnt(0)
	v_mfma_f32_32x32x16_bf16 v[32:47], v[248:251], v[140:143], v[32:47]
	v_exp_f32_e32 v86, v86
	v_exp_f32_e32 v87, v87
	v_mfma_f32_32x32x16_bf16 v[48:63], v[248:251], v[156:159], v[48:63]
	v_cvt_pk_bf16_f32 v210, v80, v81
	v_cvt_pk_bf16_f32 v211, v82, v83
	v_cvt_pk_bf16_f32 v212, v84, v85
	v_cvt_pk_bf16_f32 v213, v86, v87
	v_mfma_f32_4x4x4_16b_bf16 v[172:175], v[210:211], v[214:215], v[172:175]
	v_exp_f32_e32 v88, v88
	v_exp_f32_e32 v89, v89
	v_mfma_f32_4x4x4_16b_bf16 v[172:175], v[212:213], v[214:215], v[172:175]
	v_exp_f32_e32 v90, v90
	v_exp_f32_e32 v91, v91
	v_mfma_f32_32x32x16_bf16 v[0:15], v[210:213], v[128:131], v[0:15]
	v_exp_f32_e32 v92, v92
	v_exp_f32_e32 v93, v93
	v_exp_f32_e32 v94, v94
	v_exp_f32_e32 v95, v95
	v_mfma_f32_32x32x16_bf16 v[16:31], v[210:213], v[144:147], v[16:31]
	v_cvt_pk_bf16_f32 v248, v88, v89
	v_cvt_pk_bf16_f32 v249, v90, v91
	v_cvt_pk_bf16_f32 v250, v92, v93
	v_cvt_pk_bf16_f32 v251, v94, v95
	v_mfma_f32_4x4x4_16b_bf16 v[172:175], v[248:249], v[214:215], v[172:175]
	v_exp_f32_e32 v64, v64
	v_exp_f32_e32 v65, v65
	v_mfma_f32_4x4x4_16b_bf16 v[172:175], v[250:251], v[214:215], v[172:175]
	v_exp_f32_e32 v66, v66
	v_exp_f32_e32 v67, v67
	v_mfma_f32_32x32x16_bf16 v[0:15], v[248:251], v[132:135], v[0:15]
	v_exp_f32_e32 v68, v68
	v_exp_f32_e32 v69, v69
	v_exp_f32_e32 v70, v70
	v_exp_f32_e32 v71, v71
	v_mfma_f32_32x32x16_bf16 v[16:31], v[248:251], v[148:151], v[16:31]
	v_cvt_pk_bf16_f32 v210, v64, v65
	v_cvt_pk_bf16_f32 v211, v66, v67
	v_cvt_pk_bf16_f32 v212, v68, v69
	v_cvt_pk_bf16_f32 v213, v70, v71
	v_mfma_f32_4x4x4_16b_bf16 v[172:175], v[210:211], v[214:215], v[172:175]
	v_exp_f32_e32 v72, v72
	v_exp_f32_e32 v73, v73
	v_mfma_f32_4x4x4_16b_bf16 v[172:175], v[212:213], v[214:215], v[172:175]
	v_exp_f32_e32 v74, v74
	v_exp_f32_e32 v75, v75
	v_mfma_f32_32x32x16_bf16 v[0:15], v[210:213], v[136:139], v[0:15]
	v_exp_f32_e32 v76, v76
	v_exp_f32_e32 v77, v77
	v_exp_f32_e32 v78, v78
	v_exp_f32_e32 v79, v79
	v_mfma_f32_32x32x16_bf16 v[16:31], v[210:213], v[152:155], v[16:31]
	v_cvt_pk_bf16_f32 v248, v72, v73
	v_cvt_pk_bf16_f32 v249, v74, v75
	v_cvt_pk_bf16_f32 v250, v76, v77
	v_cvt_pk_bf16_f32 v251, v78, v79
	v_mfma_f32_4x4x4_16b_bf16 v[172:175], v[248:249], v[214:215], v[172:175]
	s_nop 1
	v_mfma_f32_4x4x4_16b_bf16 v[172:175], v[250:251], v[214:215], v[172:175]
	v_mfma_f32_32x32x16_bf16 v[0:15], v[248:251], v[140:143], v[0:15]
	v_mfma_f32_32x32x16_bf16 v[16:31], v[248:251], v[156:159], v[16:31]
	s_nop 5
	v_max3_f32 v210, v164, v165, v166
	v_max3_f32 v210, v210, v167, v172
	v_max3_f32 v210, v210, v173, v174
	v_max_f32_e32 v210, v210, v175
	v_cmp_lt_f32_e32 vcc, 0x47800000, v210
	s_cbranch_vccnz .Ldq

; __device__ __forceinline__ int crow(int r, int hi) { return (r & 3) + 8 * (r >> 2) + 4 * hi; }
; __device__ __forceinline__ float half_max(float m) { auto rr = __builtin_amdgcn_permlane32_swap(__float_as_uint(m), __float_as_uint(m), false, false); return fmaxf(__uint_as_float(rr[0]), __uint_as_float(rr[1])); }
; __device__ __forceinline__ void softmax_pv(f32x16& s0, f32x16& s1, float& mref, f32x16& negm, float& lsum, f32x16 (&o)[2], LAS float* fac, const bf16x8 (&vf)[2][4], bool first, int r32, int hi) {
;     float ma = fmaxf(fmaxf(s0[0], s0[1]), s0[2]), mb = fmaxf(fmaxf(s1[0], s1[1]), s1[2]);
; #pragma unroll
;     for (int r = 3; r < 15; r += 2) { ma = fmaxf(fmaxf(ma, s0[r]), s0[r + 1]); mb = fmaxf(fmaxf(mb, s1[r]), s1[r + 1]); }
;     float mx = fmaxf(fmaxf(ma, mb), fmaxf(s0[15], s1[15]));
;     mx = half_max(mx);
;     if (__builtin_expect(first || __any(mx > 16.0f), 0)) {
;         const float d = first ? mx : fmaxf(mx, 0.f);
;         const float f = __builtin_amdgcn_exp2f(-d);
;         lsum *= f; mref += d;
; #pragma unroll
;         for (int r = 0; r < 16; ++r) { s0[r] -= d; s1[r] -= d; negm[r] = -mref; }
;         if (hi == 0) fac[r32] = f;
;         asm volatile("s_waitcnt lgkmcnt(0)" ::: "memory");
; #pragma unroll
;         for (int r = 0; r < 16; ++r) { const float ff = fac[crow(r, hi)]; o[0][r] *= ff; o[1][r] *= ff; }
.Ldr_first_01:
	s_waitcnt lgkmcnt(0)
	v_mfma_f32_32x32x16_bf16 v[64:79], v[238:241], v[120:123], v[218:233]
	v_mfma_f32_32x32x16_bf16 v[64:79], v[188:191], v[124:127], v[64:79]
	v_mfma_f32_32x32x16_bf16 v[32:47], v[248:251], v[140:143], v[32:47]
	v_mfma_f32_32x32x16_bf16 v[48:63], v[248:251], v[156:159], v[48:63]
	s_nop 7
	s_nop 3
	v_max3_f32 v210, v80, v81, v82
	v_max3_f32 v211, v64, v65, v66
	v_max3_f32 v210, v210, v83, v84
	v_max3_f32 v211, v211, v67, v68
	v_max3_f32 v210, v210, v85, v86
	v_max3_f32 v211, v211, v69, v70
	v_max3_f32 v210, v210, v87, v88
	v_max3_f32 v211, v211, v71, v72
	v_max3_f32 v210, v210, v89, v90
	v_max3_f32 v211, v211, v73, v74
	v_max3_f32 v210, v210, v91, v92
	v_max3_f32 v211, v211, v75, v76
	v_max3_f32 v210, v210, v93, v94
	v_max3_f32 v211, v211, v77, v78
	v_max_f32_e32 v212, v95, v79
	v_max3_f32 v210, v210, v211, v212
	v_mov_b32_e32 v211, v210
	s_nop 1
	v_permlane32_swap_b32_e32 v210, v211
	v_max_f32_e32 v160, v210, v211
	v_exp_f32_e64 v246, -v160
	v_sub_f32_e32 v80, v80, v160
	v_sub_f32_e32 v64, v64, v160
	v_sub_f32_e32 v81, v81, v160
	v_sub_f32_e32 v65, v65, v160
	v_sub_f32_e32 v82, v82, v160
	v_sub_f32_e32 v66, v66, v160
	v_sub_f32_e32 v83, v83, v160
	v_sub_f32_e32 v67, v67, v160
	v_sub_f32_e32 v84, v84, v160
	v_sub_f32_e32 v68, v68, v160
	v_sub_f32_e32 v85, v85, v160
	v_sub_f32_e32 v69, v69, v160
	v_sub_f32_e32 v86, v86, v160
	v_sub_f32_e32 v70, v70, v160
	v_sub_f32_e32 v87, v87, v160
	v_sub_f32_e32 v71, v71, v160
	v_sub_f32_e32 v88, v88, v160
	v_sub_f32_e32 v72, v72, v160
	v_sub_f32_e32 v89, v89, v160
	v_sub_f32_e32 v73, v73, v160
	v_sub_f32_e32 v90, v90, v160
	v_sub_f32_e32 v74, v74, v160
	v_sub_f32_e32 v91, v91, v160
	v_sub_f32_e32 v75, v75, v160
	v_sub_f32_e32 v92, v92, v160
	v_sub_f32_e32 v76, v76, v160
	v_sub_f32_e32 v93, v93, v160
	v_sub_f32_e32 v77, v77, v160
	v_sub_f32_e32 v94, v94, v160
	v_sub_f32_e32 v78, v78, v160
	v_sub_f32_e32 v95, v95, v160
	v_sub_f32_e32 v79, v79, v160
	s_and_saveexec_b64 s[20:21], s[4:5]
	ds_write_b32 v180, v246 offset:128
	s_or_b64 exec, exec, s[20:21]
	v_add_f32_e32 v185, v185, v160
	v_xor_b32_e32 v218, 0x80000000, v185
	v_mov_b32_e32 v219, v218
	v_mov_b32_e32 v220, v218
	v_mov_b32_e32 v221, v218
	v_mov_b32_e32 v222, v218
	v_mov_b32_e32 v223, v218
	v_mov_b32_e32 v224, v218
	v_mov_b32_e32 v225, v218
	v_mov_b32_e32 v226, v218
	v_mov_b32_e32 v227, v218
	v_mov_b32_e32 v228, v218
	v_mov_b32_e32 v229, v218
	v_mov_b32_e32 v230, v218
	v_mov_b32_e32 v231, v218
	v_mov_b32_e32 v232, v218
	v_mov_b32_e32 v233, v218
	s_waitcnt lgkmcnt(0)
	v_add_u32_e32 v160, s35, v192
	ds_read_b128 v[210:213], v160 offset:128
	ds_read_b128 v[248:251], v160 offset:160
	s_waitcnt lgkmcnt(0)
	v_pk_mul_f32 v[0:1], v[0:1], v[210:211]
	v_pk_mul_f32 v[2:3], v[2:3], v[212:213]
	v_pk_mul_f32 v[4:5], v[4:5], v[248:249]
	v_pk_mul_f32 v[6:7], v[6:7], v[250:251]
	v_pk_mul_f32 v[16:17], v[16:17], v[210:211]
	v_pk_mul_f32 v[18:19], v[18:19], v[212:213]
	v_pk_mul_f32 v[20:21], v[20:21], v[248:249]
	v_pk_mul_f32 v[22:23], v[22:23], v[250:251]
	ds_read_b128 v[210:213], v160 offset:192
	ds_read_b128 v[248:251], v160 offset:224
	s_waitcnt lgkmcnt(0)
	v_pk_mul_f32 v[8:9], v[8:9], v[210:211]
	v_pk_mul_f32 v[10:11], v[10:11], v[212:213]
	v_pk_mul_f32 v[12:13], v[12:13], v[248:249]
	v_pk_mul_f32 v[14:15], v[14:15], v[250:251]
	v_pk_mul_f32 v[24:25], v[24:25], v[210:211]
	v_pk_mul_f32 v[26:27], v[26:27], v[212:213]
	v_pk_mul_f32 v[28:29], v[28:29], v[248:249]
	v_pk_mul_f32 v[30:31], v[30:31], v[250:251]
	v_exp_f32_e32 v80, v80
	v_exp_f32_e32 v81, v81
	v_exp_f32_e32 v82, v82
	v_exp_f32_e32 v83, v83
	v_exp_f32_e32 v84, v84
	v_exp_f32_e32 v85, v85
	v_exp_f32_e32 v86, v86
	v_exp_f32_e32 v87, v87
	v_cvt_pk_bf16_f32 v210, v80, v81
	v_cvt_pk_bf16_f32 v211, v82, v83
	v_cvt_pk_bf16_f32 v212, v84, v85
	v_cvt_pk_bf16_f32 v213, v86, v87
	v_mfma_f32_4x4x4_16b_bf16 v[172:175], v[210:211], v[214:215], v[172:175]
	s_branch .Ldr_join_01
